# cross-attention items mapped onto the q-projection tiles the workgroup itself produced: grid barrier before cross-attention dropped, XCD-local barrier after it (both behind the runtime placement guard
# speedup vs baseline: 1.0082x; 1.0010x over previous
; __device__ __forceinline__ unsigned xb_ld(unsigned* p)              { return __hip_atomic_load(p, __ATOMIC_RELAXED, __HIP_MEMORY_SCOPE_AGENT); }
; __device__ __forceinline__ unsigned xb_add(unsigned* p, unsigned v) { return __hip_atomic_fetch_add(p, v, __ATOMIC_RELAXED, __HIP_MEMORY_SCOPE_AGENT); }
; #define XB_SPIN(cond, bar) do { unsigned _sp = 0; while (cond) { __builtin_amdgcn_s_sleep(1); \
;     if ((++_sp & 255u) == 0u) { if (xb_ld(&(bar)[XB_TMO])) break; if (_sp > XB_SPIN_CAP) { atomicAdd(&(bar)[XB_TMO], 1u); break; } } } } while (0)
; __device__ __forceinline__ void xcd_barrier(const XcdBarrier& b, bool t0) {
;     asm volatile("s_waitcnt vmcnt(0)" ::: "memory");
;     __syncthreads();
;     if (t0) {
;         unsigned* bar = b.bar;
;         __builtin_amdgcn_s_waitcnt(0);
;         unsigned nloc = b.st[0], nx = b.st[1];
;         if (nloc == 0u) { xcd_barrier_complete(bar, b.x, nloc, nx); b.st[0] = nloc; b.st[1] = nx; }
;         const unsigned old = xb_add(&bar[XB_XSUB(b.x)], 1u);
;         const unsigned gen = old / nloc;
;         if (old + 1u == (gen + 1u) * nloc) {
;             __builtin_amdgcn_fence(__ATOMIC_RELEASE, "agent");
;             asm volatile("s_waitcnt vmcnt(0)" ::: "memory");
;             const unsigned og = xb_add(&bar[XB_TOP], 1u);
;             const unsigned tg = og / nx;
;             if (og + 1u == (tg + 1u) * nx) xb_add(&bar[XB_TOPGEN], 1u);
;             else XB_SPIN(xb_ld(&bar[XB_TOPGEN]) == tg, bar);
;             __builtin_amdgcn_fence(__ATOMIC_ACQUIRE, "agent");
;             xb_add(&bar[XB_XGEN(b.x)], 1u);
;             asm volatile("s_waitcnt vmcnt(0)" ::: "memory");
;         } else {
;             XB_SPIN(xb_ld(&bar[XB_XGEN(b.x)]) == gen, bar);
;             __builtin_amdgcn_fence(__ATOMIC_ACQUIRE, "agent");
;             asm volatile("s_waitcnt vmcnt(0)" ::: "memory");
;         }
;     }
;     __syncthreads();
; }
.LBB0_1943:
	s_waitcnt lgkmcnt(0)
	s_mov_b64 s[6:7], s[54:55]
	s_mov_b32 s0, -1
	s_getreg_b32 s8, hwreg(HW_REG_XCC_ID, 0, 4)
	s_nop 0
	v_mbcnt_lo_u32_b32 v0, s0, 0
	v_mbcnt_hi_u32_b32 v0, s0, v0
	v_or_b32_e32 v0, s97, v0
	s_waitcnt vmcnt(0)
	s_nop 0
	v_cmp_eq_u32_e32 vcc, 0, v0
	s_barrier
	s_and_saveexec_b64 s[0:1], vcc
	s_cbranch_execz .LBB0_1995
	v_readlane_b32 s9, v254, 32
	s_load_dwordx2 s[10:11], s[54:55], 0x80
	v_mov_b32_e32 v0, s9
	ds_read_b32 v2, v0
	ds_read_b32 v3, v0 offset:8
	s_waitcnt lgkmcnt(0)
	v_readfirstlane_b32 s12, v3
	v_readfirstlane_b32 s13, v2
	s_cmp_eq_u32 s12, 2
	s_cbranch_scc1 .Lxl0_full
	s_cmp_eq_u32 s13, 0
	s_cbranch_scc1 .Lxl0_full
	s_cmp_eq_u32 s12, 1
	s_cbranch_scc1 .Lxl0_go
	v_mov_b32_e32 v4, 0x1fa02000
	global_load_dwordx4 v[8:11], v4, s[10:11] sc1
	global_load_dwordx4 v[12:15], v4, s[10:11] offset:16 sc1
	global_load_dwordx4 v[16:19], v4, s[10:11] offset:32 sc1
	global_load_dwordx4 v[20:23], v4, s[10:11] offset:48 sc1
	s_lshr_b32 s16, s70, 3
	s_xor_b32 s17, s70, 0x100
	v_mov_b32_e32 v5, s17
	s_waitcnt vmcnt(0)
	v_mul_lo_u32 v6, v8, v8
	v_mul_lo_u32 v7, v9, s16
	v_sub_u32_e32 v6, v7, v6
	v_or_b32_e32 v5, v5, v6
	v_mul_lo_u32 v6, v10, v10
	v_mul_lo_u32 v7, v11, s16
	v_sub_u32_e32 v6, v7, v6
	v_or_b32_e32 v5, v5, v6
	v_mul_lo_u32 v6, v12, v12
	v_mul_lo_u32 v7, v13, s16
	v_sub_u32_e32 v6, v7, v6
	v_or_b32_e32 v5, v5, v6
	v_mul_lo_u32 v6, v14, v14
	v_mul_lo_u32 v7, v15, s16
	v_sub_u32_e32 v6, v7, v6
	v_or_b32_e32 v5, v5, v6
	v_mul_lo_u32 v6, v16, v16
	v_mul_lo_u32 v7, v17, s16
	v_sub_u32_e32 v6, v7, v6
	v_or_b32_e32 v5, v5, v6
	v_mul_lo_u32 v6, v18, v18
	v_mul_lo_u32 v7, v19, s16
	v_sub_u32_e32 v6, v7, v6
	v_or_b32_e32 v5, v5, v6
	v_mul_lo_u32 v6, v20, v20
	v_mul_lo_u32 v7, v21, s16
	v_sub_u32_e32 v6, v7, v6
	v_or_b32_e32 v5, v5, v6
	v_mul_lo_u32 v6, v22, v22
	v_mul_lo_u32 v7, v23, s16
	v_sub_u32_e32 v6, v7, v6
	v_or_b32_e32 v5, v5, v6
	s_nop 0
	v_readfirstlane_b32 s17, v5
	s_nop 3
	s_cmp_eq_u32 s17, 0
	s_cselect_b32 s12, 1, 2
	v_mov_b32_e32 v3, s12
	ds_write_b32 v0, v3 offset:8
	s_waitcnt lgkmcnt(0)
	s_cmp_eq_u32 s12, 1
	s_cbranch_scc0 .Lxl0_full

; __device__ __forceinline__ unsigned xb_ld(unsigned* p)              { return __hip_atomic_load(p, __ATOMIC_RELAXED, __HIP_MEMORY_SCOPE_AGENT); }
; __device__ __forceinline__ unsigned xb_add(unsigned* p, unsigned v) { return __hip_atomic_fetch_add(p, v, __ATOMIC_RELAXED, __HIP_MEMORY_SCOPE_AGENT); }
; #define XB_SPIN(cond, bar) do { unsigned _sp = 0; while (cond) { __builtin_amdgcn_s_sleep(1); \
;     if ((++_sp & 255u) == 0u) { if (xb_ld(&(bar)[XB_TMO])) break; if (_sp > XB_SPIN_CAP) { atomicAdd(&(bar)[XB_TMO], 1u); break; } } } } while (0)
; __device__ __forceinline__ void xcd_barrier(const XcdBarrier& b, bool t0) {
;     asm volatile("s_waitcnt vmcnt(0)" ::: "memory");
;     __syncthreads();
;     if (t0) {
;         unsigned* bar = b.bar;
;         __builtin_amdgcn_s_waitcnt(0);
;         unsigned nloc = b.st[0], nx = b.st[1];
;         if (nloc == 0u) { xcd_barrier_complete(bar, b.x, nloc, nx); b.st[0] = nloc; b.st[1] = nx; }
;         const unsigned old = xb_add(&bar[XB_XSUB(b.x)], 1u);
;         const unsigned gen = old / nloc;
;         if (old + 1u == (gen + 1u) * nloc) {
;             __builtin_amdgcn_fence(__ATOMIC_RELEASE, "agent");
;             asm volatile("s_waitcnt vmcnt(0)" ::: "memory");
;             const unsigned og = xb_add(&bar[XB_TOP], 1u);
;             const unsigned tg = og / nx;
;             if (og + 1u == (tg + 1u) * nx) xb_add(&bar[XB_TOPGEN], 1u);
;             else XB_SPIN(xb_ld(&bar[XB_TOPGEN]) == tg, bar);
;             __builtin_amdgcn_fence(__ATOMIC_ACQUIRE, "agent");
;             xb_add(&bar[XB_XGEN(b.x)], 1u);
;             asm volatile("s_waitcnt vmcnt(0)" ::: "memory");
;         } else {
;             XB_SPIN(xb_ld(&bar[XB_XGEN(b.x)]) == gen, bar);
;             __builtin_amdgcn_fence(__ATOMIC_ACQUIRE, "agent");
;             asm volatile("s_waitcnt vmcnt(0)" ::: "memory");
;         }
;     }
;     __syncthreads();
; }
.LBB0_2026:
	s_mov_b64 s[6:7], s[54:55]
	s_mov_b32 s0, -1
	s_getreg_b32 s8, hwreg(HW_REG_XCC_ID, 0, 4)
	s_nop 0
	v_mbcnt_lo_u32_b32 v0, s0, 0
	v_mbcnt_hi_u32_b32 v0, s0, v0
	v_or_b32_e32 v0, s97, v0
	s_waitcnt vmcnt(0)
	s_waitcnt lgkmcnt(0)
	v_cmp_eq_u32_e32 vcc, 0, v0
	s_barrier
	s_and_saveexec_b64 s[0:1], vcc
	s_cbranch_execz .LBB0_2078
	v_readlane_b32 s9, v254, 32
	s_nop 1
	v_mov_b32_e32 v0, s9
	ds_read_b32 v3, v0 offset:8
	s_waitcnt lgkmcnt(0)
	v_readfirstlane_b32 s12, v3
	s_nop 3
	s_cmp_eq_u32 s12, 1
	s_cbranch_scc0 .Lxs_full
	buffer_inv sc1
	s_waitcnt vmcnt(0)
	s_branch .LBB0_2078

; template <int NC, int DQK, int DV, bool CAUSAL, bool PF> ...
;     ...
;   int tid = opaque_tid(wv), wid = tid >> 6, lane = tid & 63, fr = lane & 15, fq = lane >> 4;
;   int qw0 = q0 + wid * 16, qpos = qw0 + fr;
;   bf16x8 qf[NC][NKS];
;   _Pragma("unroll") for (int c = 0; c < NC; ++c) _Pragma("unroll") for (int ks = 0; ks < NKS; ++ks)
;     qf[c][ks] = *(const bf16x8*)&Qg[(long)(wid * 16 + fr) * q_stride + c * DQK + ks * 32 + fq * 8];
;   f32x4 O[NC][NVT];
;   _Pragma("unroll") for (int c = 0; c < NC; ++c) _Pragma("unroll") for (int v = 0; v < NVT; ++v) O[c][v] = f32x4{0.f, 0.f, 0.f, 0.f};
;   float mrun[NC], lsum[NC];
;   _Pragma("unroll") for (int c = 0; c < NC; ++c) { mrun[c] = -1e30f; lsum[c] = 0.f; }
;   const __amdgpu_buffer_rsrc_t rsK = __builtin_amdgcn_make_buffer_rsrc((void*)Kg, 0, 0x7fffffff, 0x00020000);
;   const __amdgpu_buffer_rsrc_t rsV = __builtin_amdgcn_make_buffer_rsrc((void*)VTg, 0, 0x7fffffff, 0x00020000);
;   const __amdgpu_buffer_rsrc_t rsNK = __builtin_amdgcn_make_buffer_rsrc((void*)nKg, 0, 0x7fffffff, 0x00020000);
;   const __amdgpu_buffer_rsrc_t rsNV = __builtin_amdgcn_make_buffer_rsrc((void*)nVTg, 0, 0x7fffffff, 0x00020000);
;   int kvo[KPT], vvo[VPT];
;   _Pragma("unroll") for (int i = 0; i < KPT; ++i) { int id = tid + i * 512, row = id / KCH, cc = id % KCH; kvo[i] = (row * k_stride + cc * 8) * 2; }
;   _Pragma("unroll") for (int i = 0; i < VPT; ++i) { int id = tid + i * 512, row = id >> 3, cc = id & 7; vvo[i] = (row * vt_stride + cc * 8) * 2; }
;     ...
;   if (PF && !pre0) FA_PREFETCH(0);
; __device__ __forceinline__ void cross_attn_phase(const Params& p, int layer, char* shm, int wv) {
;     ...
;   for (int i = blockIdx.x; i < 1024; i += gridDim.x) {
;     int head = i & 3, blk = i >> 2, b = blk >> 6, qblk = blk & 63;
;     __syncthreads();
;     flash_item<1, 256, 256, false, true>(caq + ((long)(b * SEQ + qblk * 128)) * DM + head * 256, DM, mK + ((long)b * MEML) * DM + head * 256, DM,
;                                    mVT + ((long)(b * DM + head * 256)) * MEML, MEML, 4, 0, 0.0625f * LOG2E, nullptr, 0.f, nullptr, 1.f,
;                                    cao + ((long)(b * SEQ + qblk * 128)) * DM + head * 256, DM, shm, wv,
;                                    ckreg, cvreg, false, nullptr, nullptr, false);
;   }
.LBB0_2081:
	v_readlane_b32 s21, v254, 32
	s_nop 1
	v_mov_b32_e32 v0, s21
	ds_read_b32 v0, v0 offset:8
	s_waitcnt lgkmcnt(0)
	v_readfirstlane_b32 s8, v0
	s_mov_b32 s21, s18
	s_nop 2
	s_cmp_eq_u32 s8, 1
	s_cbranch_scc0 .Lxq_nomap
	s_lshr_b32 s0, s18, 8
	s_lshr_b32 s1, s0, 1
	s_and_b32 s0, s0, 1
	s_and_b32 s8, s72, 7
	s_lshl_b32 s8, s8, 1
	s_add_i32 s8, s8, s1
	s_lshl_b32 s8, s8, 3
	s_lshr_b32 s1, s72, 3
	s_and_b32 s1, s1, 7
	s_add_i32 s8, s8, s1
	s_lshl_b32 s8, s8, 1
	s_add_i32 s8, s8, s0
	s_lshl_b32 s8, s8, 2
	s_lshr_b32 s1, s72, 6
	s_or_b32 s21, s8, s1
.Lxq_nomap:
	s_ashr_i32 s8, s21, 8
	s_lshl_b32 s1, s21, 5
	s_lshl_b32 s0, s8, 13
	s_and_b32 s1, s1, 0x1f80
	s_or_b32 s10, s0, s1
	s_ashr_i32 s11, s10, 31
	s_lshl_b64 s[0:1], s[10:11], 10
	s_lshl_b64 s[10:11], s[10:11], 11
	s_add_u32 s9, s6, s10
	s_addc_u32 s11, s7, s11
	s_lshl_b32 s10, s21, 8
	s_and_b32 s19, s10, 0x300
	s_lshl_b32 s22, s19, 1
	s_add_u32 s10, s9, s22
	s_addc_u32 s11, s11, 0
	s_ashr_i32 s9, s8, 31
	s_lshl_b64 s[20:21], s[8:9], 19
	s_add_u32 s9, s14, s20
	s_addc_u32 s20, s15, s21
	s_mov_b32 s21, -1
	s_barrier
	s_add_u32 s80, s9, s22
	v_mbcnt_lo_u32_b32 v0, s21, 0
	v_mbcnt_hi_u32_b32 v0, s21, v0
	v_or_b32_e32 v2, s97, v0
	s_addc_u32 s20, s20, 0
	v_ashrrev_i32_e32 v0, 2, v2
	v_bfi_b32 v0, -16, v0, v2
	v_ashrrev_i32_e32 v1, 31, v0
	v_lshlrev_b64 v[146:147], 11, v[0:1]
	v_lshl_add_u64 v[0:1], s[10:11], 0, v[146:147]
	v_and_b32_e32 v32, 48, v2
	v_lshl_add_u64 v[0:1], v[0:1], 0, v[32:33]
	global_load_dwordx4 v[94:97], v[0:1], off
	global_load_dwordx4 v[90:93], v[0:1], off offset:64
	global_load_dwordx4 v[86:89], v[0:1], off offset:128
	global_load_dwordx4 v[82:85], v[0:1], off offset:192
	global_load_dwordx4 v[78:81], v[0:1], off offset:256
	global_load_dwordx4 v[74:77], v[0:1], off offset:320
	global_load_dwordx4 v[70:73], v[0:1], off offset:384
	global_load_dwordx4 v[66:69], v[0:1], off offset:448
	v_ashrrev_i32_e32 v0, 31, v2
	v_lshrrev_b32_e32 v0, 27, v0
	v_add_u32_e32 v0, v2, v0
	v_ashrrev_i32_e32 v1, 5, v0
	v_and_b32_e32 v0, 0xfffffe0, v0
	v_sub_u32_e32 v0, v2, v0
	v_lshlrev_b32_e32 v153, 4, v0
	v_add_u32_e32 v0, 0x200, v2
	v_ashrrev_i32_e32 v3, 31, v0
	v_lshrrev_b32_e32 v3, 27, v3
	v_add_u32_e32 v3, v0, v3
	s_waitcnt vmcnt(14)
	v_ashrrev_i32_e32 v4, 5, v3
	v_and_b32_e32 v3, 0xfffffe0, v3
	v_sub_u32_e32 v3, v0, v3
	v_lshlrev_b32_e32 v155, 4, v3
	v_add_u32_e32 v3, 0x400, v2
	v_ashrrev_i32_e32 v5, 31, v3
	v_lshrrev_b32_e32 v5, 27, v5
	v_add_u32_e32 v5, v3, v5
	v_ashrrev_i32_e32 v6, 5, v5
	v_and_b32_e32 v5, 0xfffffe0, v5
	v_sub_u32_e32 v5, v3, v5
	v_lshlrev_b32_e32 v157, 4, v5
	v_add_u32_e32 v5, 0x600, v2
	v_ashrrev_i32_e32 v7, 31, v5
	s_lshl_b32 s8, s8, 10
	v_lshrrev_b32_e32 v7, 27, v7
	s_or_b32 s8, s8, s19
	v_add_u32_e32 v7, v5, v7
	s_ashr_i32 s9, s8, 31
	s_waitcnt vmcnt(13)
	v_ashrrev_i32_e32 v8, 5, v7
	v_and_b32_e32 v7, 0xfffffe0, v7
	s_lshl_b64 s[8:9], s[8:9], 9
	v_sub_u32_e32 v7, v5, v7
	v_lshlrev_b32_e32 v9, 3, v2
	s_add_u32 s8, s16, s8
	v_lshlrev_b32_e32 v159, 4, v7
	v_lshlrev_b32_e32 v7, 5, v2
	v_and_b32_e32 v10, 56, v9
	s_mov_b32 s10, 0x7fffff00
	s_addc_u32 s9, s17, s9
	s_mov_b32 s83, 0x20000
	v_and_or_b32 v7, v7, s10, v10
	s_and_b32 s81, s20, 0xffff
	v_lshl_add_u32 v154, v1, 11, v153
	v_lshlrev_b32_e32 v161, 1, v7
	s_and_b32 s9, s9, 0xffff
	s_mov_b32 s10, s82
	s_mov_b32 s11, s83
	v_lshl_add_u32 v156, v4, 11, v155
	v_lshl_add_u32 v158, v6, 11, v157
	v_lshl_add_u32 v160, v8, 11, v159
	v_add_u32_e32 v166, 0x8000, v161
	v_add_u32_e32 v167, 0x10000, v161
	v_add_u32_e32 v168, 0x18000, v161
	buffer_load_dwordx4 v[126:129], v154, s[80:83], 0 offen
	buffer_load_dwordx4 v[122:125], v156, s[80:83], 0 offen
	buffer_load_dwordx4 v[118:121], v158, s[80:83], 0 offen
	buffer_load_dwordx4 v[114:117], v160, s[80:83], 0 offen
	buffer_load_dwordx4 v[110:113], v161, s[8:11], 0 offen
	buffer_load_dwordx4 v[106:109], v166, s[8:11], 0 offen
	buffer_load_dwordx4 v[102:105], v167, s[8:11], 0 offen
	buffer_load_dwordx4 v[98:101], v168, s[8:11], 0 offen
	s_movk_i32 s10, 0x210
	v_mul_lo_u32 v188, v1, s10
	v_mul_lo_u32 v187, v4, s10
	v_mul_lo_u32 v175, v6, s10
	v_mul_lo_u32 v186, v8, s10
	s_movk_i32 s10, 0x90
	v_lshrrev_b32_e32 v0, 3, v0
	v_and_b32_e32 v7, 63, v2
	v_and_b32_e32 v170, 32, v9
	v_lshlrev_b32_e32 v9, 4, v2
	v_lshlrev_b32_e32 v11, 1, v2
	v_mul_lo_u32 v173, v0, s10
	v_lshrrev_b32_e32 v0, 3, v3
	v_and_b32_e32 v10, 15, v2
	v_and_b32_e32 v9, 16, v9
	v_and_b32_e32 v11, 4, v11
	v_lshlrev_b32_e32 v7, 2, v7
	v_lshrrev_b32_e32 v1, 3, v2
	v_mul_lo_u32 v172, v0, s10
	v_lshrrev_b32_e32 v0, 3, v5
	v_mov_b32_e32 v38, v33
	v_mov_b32_e32 v39, v33
	v_mov_b32_e32 v40, v33
	v_mov_b32_e32 v41, v33
	v_bfe_u32 v148, v2, 4, 2
	v_xor_b32_e32 v149, 0x80, v7
	v_mul_lo_u32 v174, v1, s10
	v_mul_lo_u32 v171, v0, s10
	v_mul_u32_u24_e32 v169, 0x210, v10
	v_mul_u32_u24_e32 v151, 0x90, v10
	v_lshlrev_b32_e32 v189, 1, v9
	v_lshlrev_b32_e32 v190, 1, v11
	v_mov_b64_e32 v[48:49], v[40:41]
	s_waitcnt vmcnt(20)
	v_mov_b64_e32 v[52:53], v[40:41]
	v_mov_b64_e32 v[56:57], v[40:41]
	v_mov_b64_e32 v[60:61], v[40:41]
	v_mov_b64_e32 v[64:65], v[40:41]
	v_mov_b64_e32 v[44:45], v[40:41]
	v_mov_b64_e32 v[34:35], v[38:39]
	v_mov_b64_e32 v[28:29], v[38:39]
	v_mov_b64_e32 v[24:25], v[38:39]
	v_mov_b64_e32 v[20:21], v[38:39]
	v_mov_b64_e32 v[16:17], v[38:39]
	v_mov_b64_e32 v[12:13], v[38:39]
	v_mov_b64_e32 v[8:9], v[38:39]
	v_mov_b64_e32 v[4:5], v[38:39]
	v_mov_b64_e32 v[0:1], v[38:39]
	s_mov_b32 s20, 0
	s_movk_i32 s21, 0x80
	v_mov_b32_e32 v152, 0xf149f2ca
	v_mov_b32_e32 v150, 0
	s_mov_b32 s22, s83
	v_mov_b64_e32 v[46:47], v[38:39]
	v_mov_b64_e32 v[50:51], v[38:39]
	v_mov_b64_e32 v[54:55], v[38:39]
	v_mov_b64_e32 v[58:59], v[38:39]
	v_mov_b64_e32 v[62:63], v[38:39]
	v_mov_b64_e32 v[42:43], v[38:39]
	v_mov_b64_e32 v[36:37], v[40:41]
	v_mov_b64_e32 v[30:31], v[40:41]
	v_mov_b64_e32 v[26:27], v[40:41]
	v_mov_b64_e32 v[22:23], v[40:41]
	v_mov_b64_e32 v[18:19], v[40:41]
	v_mov_b64_e32 v[14:15], v[40:41]
	v_mov_b64_e32 v[10:11], v[40:41]
	v_mov_b64_e32 v[6:7], v[40:41]
	v_mov_b64_e32 v[2:3], v[40:41]
	s_branch .LBB0_2083

; __device__ __forceinline__ unsigned xb_ld(unsigned* p)              { return __hip_atomic_load(p, __ATOMIC_RELAXED, __HIP_MEMORY_SCOPE_AGENT); }
; __device__ __forceinline__ unsigned xb_add(unsigned* p, unsigned v) { return __hip_atomic_fetch_add(p, v, __ATOMIC_RELAXED, __HIP_MEMORY_SCOPE_AGENT); }
; #define XB_SPIN(cond, bar) do { unsigned _sp = 0; while (cond) { __builtin_amdgcn_s_sleep(1); \
;     if ((++_sp & 255u) == 0u) { if (xb_ld(&(bar)[XB_TMO])) break; if (_sp > XB_SPIN_CAP) { atomicAdd(&(bar)[XB_TMO], 1u); break; } } } } while (0)
; __device__ __forceinline__ void xcd_barrier(const XcdBarrier& b, bool t0) {
;     asm volatile("s_waitcnt vmcnt(0)" ::: "memory");
;     __syncthreads();
;     if (t0) {
;         unsigned* bar = b.bar;
;         __builtin_amdgcn_s_waitcnt(0);
;         unsigned nloc = b.st[0], nx = b.st[1];
;         if (nloc == 0u) { xcd_barrier_complete(bar, b.x, nloc, nx); b.st[0] = nloc; b.st[1] = nx; }
;         const unsigned old = xb_add(&bar[XB_XSUB(b.x)], 1u);
;         const unsigned gen = old / nloc;
;         if (old + 1u == (gen + 1u) * nloc) {
;             __builtin_amdgcn_fence(__ATOMIC_RELEASE, "agent");
;             asm volatile("s_waitcnt vmcnt(0)" ::: "memory");
;             const unsigned og = xb_add(&bar[XB_TOP], 1u);
;             const unsigned tg = og / nx;
;             if (og + 1u == (tg + 1u) * nx) xb_add(&bar[XB_TOPGEN], 1u);
;             else XB_SPIN(xb_ld(&bar[XB_TOPGEN]) == tg, bar);
;             __builtin_amdgcn_fence(__ATOMIC_ACQUIRE, "agent");
;             xb_add(&bar[XB_XGEN(b.x)], 1u);
;             asm volatile("s_waitcnt vmcnt(0)" ::: "memory");
;         } else {
;             XB_SPIN(xb_ld(&bar[XB_XGEN(b.x)]) == gen, bar);
;             __builtin_amdgcn_fence(__ATOMIC_ACQUIRE, "agent");
;             asm volatile("s_waitcnt vmcnt(0)" ::: "memory");
;         }
;     }
;     __syncthreads();
; }
.LBB0_2087:
	s_mov_b64 s[6:7], s[54:55]
	s_mov_b32 s0, -1
	s_getreg_b32 s8, hwreg(HW_REG_XCC_ID, 0, 4)
	s_nop 0
	v_mbcnt_lo_u32_b32 v0, s0, 0
	v_mbcnt_hi_u32_b32 v0, s0, v0
	v_or_b32_e32 v0, s97, v0
	s_waitcnt vmcnt(0)
	s_nop 0
	v_cmp_eq_u32_e32 vcc, 0, v0
	s_barrier
	s_and_saveexec_b64 s[0:1], vcc
	s_cbranch_execz .LBB0_2139
	v_readlane_b32 s9, v254, 32
	s_load_dwordx2 s[10:11], s[54:55], 0x80
	v_mov_b32_e32 v0, s9
	ds_read_b32 v2, v0
	ds_read_b32 v3, v0 offset:8
	s_waitcnt lgkmcnt(0)
	v_readfirstlane_b32 s12, v3
	v_readfirstlane_b32 s13, v2
	s_cmp_eq_u32 s12, 2
	s_cbranch_scc1 .Lxl3_full
	s_cmp_eq_u32 s13, 0
	s_cbranch_scc1 .Lxl3_full
	s_cmp_eq_u32 s12, 1
	s_cbranch_scc1 .Lxl3_go
	v_mov_b32_e32 v4, 0x1fa02000
	global_load_dwordx4 v[8:11], v4, s[10:11] sc1
	global_load_dwordx4 v[12:15], v4, s[10:11] offset:16 sc1
	global_load_dwordx4 v[16:19], v4, s[10:11] offset:32 sc1
	global_load_dwordx4 v[20:23], v4, s[10:11] offset:48 sc1
	s_lshr_b32 s16, s70, 3
	s_xor_b32 s17, s70, 0x100
	v_mov_b32_e32 v5, s17
	s_waitcnt vmcnt(0)
	v_mul_lo_u32 v6, v8, v8
	v_mul_lo_u32 v7, v9, s16
	v_sub_u32_e32 v6, v7, v6
	v_or_b32_e32 v5, v5, v6
	v_mul_lo_u32 v6, v10, v10
	v_mul_lo_u32 v7, v11, s16
	v_sub_u32_e32 v6, v7, v6
	v_or_b32_e32 v5, v5, v6
	v_mul_lo_u32 v6, v12, v12
	v_mul_lo_u32 v7, v13, s16
	v_sub_u32_e32 v6, v7, v6
	v_or_b32_e32 v5, v5, v6
	v_mul_lo_u32 v6, v14, v14
	v_mul_lo_u32 v7, v15, s16
	v_sub_u32_e32 v6, v7, v6
	v_or_b32_e32 v5, v5, v6
	v_mul_lo_u32 v6, v16, v16
	v_mul_lo_u32 v7, v17, s16
	v_sub_u32_e32 v6, v7, v6
	v_or_b32_e32 v5, v5, v6
	v_mul_lo_u32 v6, v18, v18
	v_mul_lo_u32 v7, v19, s16
	v_sub_u32_e32 v6, v7, v6
	v_or_b32_e32 v5, v5, v6
	v_mul_lo_u32 v6, v20, v20
	v_mul_lo_u32 v7, v21, s16
	v_sub_u32_e32 v6, v7, v6
	v_or_b32_e32 v5, v5, v6
	v_mul_lo_u32 v6, v22, v22
	v_mul_lo_u32 v7, v23, s16
	v_sub_u32_e32 v6, v7, v6
	v_or_b32_e32 v5, v5, v6
	s_nop 0
	v_readfirstlane_b32 s17, v5
	s_nop 3
	s_cmp_eq_u32 s17, 0
	s_cselect_b32 s12, 1, 2
	v_mov_b32_e32 v3, s12
	ds_write_b32 v0, v3 offset:8
	s_waitcnt lgkmcnt(0)
	s_cmp_eq_u32 s12, 1
	s_cbranch_scc0 .Lxl3_full

; __device__ __forceinline__ unsigned xb_ld(unsigned* p)              { return __hip_atomic_load(p, __ATOMIC_RELAXED, __HIP_MEMORY_SCOPE_AGENT); }
; __device__ __forceinline__ unsigned xb_add(unsigned* p, unsigned v) { return __hip_atomic_fetch_add(p, v, __ATOMIC_RELAXED, __HIP_MEMORY_SCOPE_AGENT); }
; #define XB_SPIN(cond, bar) do { unsigned _sp = 0; while (cond) { __builtin_amdgcn_s_sleep(1); \
;     if ((++_sp & 255u) == 0u) { if (xb_ld(&(bar)[XB_TMO])) break; if (_sp > XB_SPIN_CAP) { atomicAdd(&(bar)[XB_TMO], 1u); break; } } } } while (0)
; __device__ __forceinline__ void xcd_barrier(const XcdBarrier& b, bool t0) {
;     asm volatile("s_waitcnt vmcnt(0)" ::: "memory");
;     __syncthreads();
;     if (t0) {
;         unsigned* bar = b.bar;
;         __builtin_amdgcn_s_waitcnt(0);
;         unsigned nloc = b.st[0], nx = b.st[1];
;         if (nloc == 0u) { xcd_barrier_complete(bar, b.x, nloc, nx); b.st[0] = nloc; b.st[1] = nx; }
;         const unsigned old = xb_add(&bar[XB_XSUB(b.x)], 1u);
;         const unsigned gen = old / nloc;
;         if (old + 1u == (gen + 1u) * nloc) {
;             __builtin_amdgcn_fence(__ATOMIC_RELEASE, "agent");
;             asm volatile("s_waitcnt vmcnt(0)" ::: "memory");
;             const unsigned og = xb_add(&bar[XB_TOP], 1u);
;             const unsigned tg = og / nx;
;             if (og + 1u == (tg + 1u) * nx) xb_add(&bar[XB_TOPGEN], 1u);
;             else XB_SPIN(xb_ld(&bar[XB_TOPGEN]) == tg, bar);
;             __builtin_amdgcn_fence(__ATOMIC_ACQUIRE, "agent");
;             xb_add(&bar[XB_XGEN(b.x)], 1u);
;             asm volatile("s_waitcnt vmcnt(0)" ::: "memory");
;         } else {
;             XB_SPIN(xb_ld(&bar[XB_XGEN(b.x)]) == gen, bar);
;             __builtin_amdgcn_fence(__ATOMIC_ACQUIRE, "agent");
;             asm volatile("s_waitcnt vmcnt(0)" ::: "memory");
;         }
;     }
;     __syncthreads();
; }
.LBB0_2261:
	s_mov_b64 s[6:7], s[54:55]
	s_mov_b32 s0, -1
	s_getreg_b32 s8, hwreg(HW_REG_XCC_ID, 0, 4)
	s_nop 0
	v_mbcnt_lo_u32_b32 v0, s0, 0
	v_mbcnt_hi_u32_b32 v0, s0, v0
	v_or_b32_e32 v0, s97, v0
	s_waitcnt vmcnt(0)
	s_waitcnt lgkmcnt(0)
	v_cmp_eq_u32_e32 vcc, 0, v0
	s_barrier
	s_and_saveexec_b64 s[0:1], vcc
	s_cbranch_execz .LBB0_2313
	v_readlane_b32 s9, v254, 32
	s_load_dwordx2 s[10:11], s[54:55], 0x80
	v_mov_b32_e32 v0, s9
	ds_read_b32 v2, v0
	ds_read_b32 v3, v0 offset:8
	s_waitcnt lgkmcnt(0)
	v_readfirstlane_b32 s12, v3
	v_readfirstlane_b32 s13, v2
	s_cmp_eq_u32 s12, 2
	s_cbranch_scc1 .Lxl2_full
	s_cmp_eq_u32 s13, 0
	s_cbranch_scc1 .Lxl2_full
	s_cmp_eq_u32 s12, 1
	s_cbranch_scc1 .Lxl2_go
	v_mov_b32_e32 v4, 0x1fa02000
	global_load_dwordx4 v[8:11], v4, s[10:11] sc1
	global_load_dwordx4 v[12:15], v4, s[10:11] offset:16 sc1
	global_load_dwordx4 v[16:19], v4, s[10:11] offset:32 sc1
	global_load_dwordx4 v[20:23], v4, s[10:11] offset:48 sc1
	s_lshr_b32 s16, s70, 3
	s_xor_b32 s17, s70, 0x100
	v_mov_b32_e32 v5, s17
	s_waitcnt vmcnt(0)
	v_mul_lo_u32 v6, v8, v8
	v_mul_lo_u32 v7, v9, s16
	v_sub_u32_e32 v6, v7, v6
	v_or_b32_e32 v5, v5, v6
	v_mul_lo_u32 v6, v10, v10
	v_mul_lo_u32 v7, v11, s16
	v_sub_u32_e32 v6, v7, v6
	v_or_b32_e32 v5, v5, v6
	v_mul_lo_u32 v6, v12, v12
	v_mul_lo_u32 v7, v13, s16
	v_sub_u32_e32 v6, v7, v6
	v_or_b32_e32 v5, v5, v6
	v_mul_lo_u32 v6, v14, v14
	v_mul_lo_u32 v7, v15, s16
	v_sub_u32_e32 v6, v7, v6
	v_or_b32_e32 v5, v5, v6
	v_mul_lo_u32 v6, v16, v16
	v_mul_lo_u32 v7, v17, s16
	v_sub_u32_e32 v6, v7, v6
	v_or_b32_e32 v5, v5, v6
	v_mul_lo_u32 v6, v18, v18
	v_mul_lo_u32 v7, v19, s16
	v_sub_u32_e32 v6, v7, v6
	v_or_b32_e32 v5, v5, v6
	v_mul_lo_u32 v6, v20, v20
	v_mul_lo_u32 v7, v21, s16
	v_sub_u32_e32 v6, v7, v6
	v_or_b32_e32 v5, v5, v6
	v_mul_lo_u32 v6, v22, v22
	v_mul_lo_u32 v7, v23, s16
	v_sub_u32_e32 v6, v7, v6
	v_or_b32_e32 v5, v5, v6
	s_nop 0
	v_readfirstlane_b32 s17, v5
	s_nop 3
	s_cmp_eq_u32 s17, 0
	s_cselect_b32 s12, 1, 2
	v_mov_b32_e32 v3, s12
	ds_write_b32 v0, v3 offset:8
	s_waitcnt lgkmcnt(0)
	s_cmp_eq_u32 s12, 1
	s_cbranch_scc0 .Lxl2_full
